# A loop hand-pipelined + B: exact counted vmcnt (2-unit prefetch depth) and V-fragment LDS reads hoisted above the softmax section
# baseline (speedup 1.0000x reference)
.LBB0_138:
	s_lshl_b32 s68, s84, 6
	v_subrev_u32_e32 v0, s68, v160
	v_add_u32_e32 v2, s68, v160
	v_max_i32_e32 v0, 0, v0
	v_min_i32_e32 v2, 0xfff, v2
	v_sub_u32_e32 v2, v2, v0
	v_lshl_or_b32 v3, s85, 5, v170
	v_add_u32_e32 v0, s68, v0
	v_sub_u32_e32 v0, v167, v0
	v_mul_lo_u32 v3, v3, s84
	s_nop 0
	v_exp_f32_e32 v5, v64
	v_add_u32_e32 v4, v0, v3
	v_add3_u32 v0, v3, s84, v0
	v_exp_f32_e32 v3, v65
	v_exp_f32_e32 v6, v66
	v_cmp_le_u32_e32 vcc, v4, v2
	v_exp_f32_e32 v7, v67
	v_exp_f32_e32 v8, v68
	v_cndmask_b32_e32 v4, 0, v5, vcc
	v_cmp_le_u32_e32 vcc, v0, v2
	v_add_u32_e32 v0, s84, v0
	v_add_f32_e32 v5, 0, v4
	v_cndmask_b32_e32 v3, 0, v3, vcc
	v_cmp_le_u32_e32 vcc, v0, v2
	v_add_u32_e32 v0, s84, v0
	s_mul_i32 s68, s84, 5
	v_exp_f32_e32 v9, v69
	v_add_f32_e32 v5, v3, v5
	v_cndmask_b32_e32 v6, 0, v6, vcc
	v_cmp_le_u32_e32 vcc, v0, v2
	v_add_u32_e32 v0, s68, v0
	v_exp_f32_e32 v10, v70
	v_add_f32_e32 v5, v6, v5
	v_cndmask_b32_e32 v7, 0, v7, vcc
	v_cmp_le_u32_e32 vcc, v0, v2
	v_add_u32_e32 v0, s84, v0
	v_exp_f32_e32 v11, v71
	v_add_f32_e32 v5, v7, v5
	v_cndmask_b32_e32 v8, 0, v8, vcc
	v_cmp_le_u32_e32 vcc, v0, v2
	v_add_u32_e32 v0, s84, v0
	v_exp_f32_e32 v12, v72
	v_add_f32_e32 v5, v8, v5
	v_cndmask_b32_e32 v9, 0, v9, vcc
	v_cmp_le_u32_e32 vcc, v0, v2
	v_add_u32_e32 v0, s84, v0
	v_exp_f32_e32 v13, v73
	v_add_f32_e32 v5, v9, v5
	v_cndmask_b32_e32 v10, 0, v10, vcc
	v_cmp_le_u32_e32 vcc, v0, v2
	v_add_u32_e32 v0, s68, v0
	v_exp_f32_e32 v14, v74
	v_add_f32_e32 v5, v10, v5
	v_cndmask_b32_e32 v11, 0, v11, vcc
	v_cmp_le_u32_e32 vcc, v0, v2
	v_add_u32_e32 v0, s84, v0
	v_exp_f32_e32 v15, v75
	v_add_f32_e32 v5, v11, v5
	v_cndmask_b32_e32 v12, 0, v12, vcc
	v_cmp_le_u32_e32 vcc, v0, v2
	v_add_u32_e32 v0, s84, v0
	v_exp_f32_e32 v64, v76
	v_add_f32_e32 v5, v12, v5
	v_cndmask_b32_e32 v13, 0, v13, vcc
	v_cmp_le_u32_e32 vcc, v0, v2
	v_add_u32_e32 v0, s84, v0
	v_exp_f32_e32 v65, v77
	v_add_f32_e32 v5, v13, v5
	v_cndmask_b32_e32 v14, 0, v14, vcc
	v_cmp_le_u32_e32 vcc, v0, v2
	v_add_u32_e32 v0, s68, v0
	v_exp_f32_e32 v66, v78
	v_add_f32_e32 v5, v14, v5
	v_cndmask_b32_e32 v15, 0, v15, vcc
	v_cmp_le_u32_e32 vcc, v0, v2
	v_add_u32_e32 v0, s84, v0
	v_exp_f32_e32 v67, v79
	v_add_f32_e32 v5, v15, v5
	v_cndmask_b32_e32 v64, 0, v64, vcc
	v_cmp_le_u32_e32 vcc, v0, v2
	v_add_u32_e32 v0, s84, v0
	v_add_f32_e32 v5, v64, v5
	v_cndmask_b32_e32 v65, 0, v65, vcc
	v_cmp_le_u32_e32 vcc, v0, v2
	v_add_u32_e32 v0, s84, v0
	v_add_f32_e32 v5, v65, v5
	v_cndmask_b32_e32 v66, 0, v66, vcc
	v_cmp_le_u32_e32 vcc, v0, v2
	v_add_f32_e32 v5, v66, v5
	s_waitcnt lgkmcnt(0)
	s_nop 0
	v_cndmask_b32_e32 v0, 0, v67, vcc
	v_add_f32_e32 v2, v0, v5
	v_add_f32_e32 v171, v171, v2
	v_cvt_pk_bf16_f32 v2, v4, v3
	v_cvt_pk_bf16_f32 v3, v6, v7
	v_cvt_pk_bf16_f32 v5, v10, v11
	v_cvt_pk_bf16_f32 v6, v12, v13
	v_cvt_pk_bf16_f32 v4, v8, v9
	v_cvt_pk_bf16_f32 v7, v14, v15
	v_cvt_pk_bf16_f32 v8, v64, v65
	v_cvt_pk_bf16_f32 v9, v66, v0
	s_nop 1
	v_mfma_f32_32x32x16_bf16 v[32:47], v[180:183], v[2:5], v[32:47]
	v_mfma_f32_32x32x16_bf16 v[32:47], v[184:187], v[6:9], v[32:47]
	v_mfma_f32_32x32x16_bf16 v[16:31], v[188:191], v[2:5], v[16:31]
	v_mfma_f32_32x32x16_bf16 v[16:31], v[192:195], v[6:9], v[16:31]

.LBB0_145:
	s_cmp_lt_u32 s93, 32
	s_cbranch_scc1 .Lmyb_cnt_e
	s_waitcnt vmcnt(0)
.Lmyb_cnt_e:
	s_waitcnt vmcnt(12)
	v_mfma_f32_32x32x16_bf16 v[64:79], v[96:99], v[80:83], v[48:63]
	s_cmp_gt_u32 s93, 30
	s_cselect_b64 s[4:5], -1, 0
	s_and_b64 vcc, exec, s[4:5]
	s_waitcnt vmcnt(11)
	ds_write_b128 v172, v[112:115]
	s_waitcnt vmcnt(10)
	ds_write_b128 v173, v[116:119]
	s_waitcnt vmcnt(9)
	ds_write_b128 v174, v[136:139]
	s_waitcnt vmcnt(8)
	ds_write_b128 v175, v[140:143]
	v_mfma_f32_32x32x16_bf16 v[64:79], v[100:103], v[84:87], v[64:79]
	ds_read_b64_tr_b16 v[180:181], v176
	ds_read_b64_tr_b16 v[182:183], v176 offset:1152
	v_mfma_f32_32x32x16_bf16 v[64:79], v[104:107], v[88:91], v[64:79]
	ds_read_b64_tr_b16 v[184:185], v176 offset:2304
	ds_read_b64_tr_b16 v[186:187], v176 offset:3456
	ds_read_b64_tr_b16 v[188:189], v176 offset:64
	ds_read_b64_tr_b16 v[190:191], v176 offset:1216
	v_mfma_f32_32x32x16_bf16 v[64:79], v[108:111], v[92:95], v[64:79]
	ds_read_b64_tr_b16 v[192:193], v176 offset:2368
	ds_read_b64_tr_b16 v[194:195], v176 offset:3520
	s_cbranch_vccnz .LBB0_153
	s_cmp_lt_u32 s93, 18
	s_cbranch_scc1 .LBB0_151
	s_cmp_gt_u32 s93, 25
	s_mov_b64 s[68:69], -1
	s_cbranch_scc0 .LBB0_149
	s_sub_i32 s94, s93, 26
	s_mov_b64 s[68:69], 0

.LBB0_153:
	s_lshl_b32 s68, s86, 6
	v_subrev_u32_e32 v0, s68, v160
	v_add_u32_e32 v2, s68, v160
	v_max_i32_e32 v0, 0, v0
	v_min_i32_e32 v2, 0xfff, v2
	v_sub_u32_e32 v2, v2, v0
	v_lshl_or_b32 v3, s87, 5, v170
	v_add_u32_e32 v0, s68, v0
	v_sub_u32_e32 v0, v167, v0
	v_mul_lo_u32 v3, v3, s86
	s_nop 0
	v_exp_f32_e32 v5, v64
	v_add_u32_e32 v4, v0, v3
	v_add3_u32 v0, v3, s86, v0
	v_exp_f32_e32 v3, v65
	v_exp_f32_e32 v6, v66
	v_cmp_le_u32_e32 vcc, v4, v2
	v_exp_f32_e32 v7, v67
	v_exp_f32_e32 v8, v68
	v_cndmask_b32_e32 v4, 0, v5, vcc
	v_cmp_le_u32_e32 vcc, v0, v2
	v_add_u32_e32 v0, s86, v0
	v_add_f32_e32 v5, 0, v4
	v_cndmask_b32_e32 v3, 0, v3, vcc
	v_cmp_le_u32_e32 vcc, v0, v2
	v_add_u32_e32 v0, s86, v0
	s_mul_i32 s68, s86, 5
	v_exp_f32_e32 v9, v69
	v_add_f32_e32 v5, v3, v5
	v_cndmask_b32_e32 v6, 0, v6, vcc
	v_cmp_le_u32_e32 vcc, v0, v2
	v_add_u32_e32 v0, s68, v0
	v_exp_f32_e32 v10, v70
	v_add_f32_e32 v5, v6, v5
	v_cndmask_b32_e32 v7, 0, v7, vcc
	v_cmp_le_u32_e32 vcc, v0, v2
	v_add_u32_e32 v0, s86, v0
	v_exp_f32_e32 v11, v71
	v_add_f32_e32 v5, v7, v5
	v_cndmask_b32_e32 v8, 0, v8, vcc
	v_cmp_le_u32_e32 vcc, v0, v2
	v_add_u32_e32 v0, s86, v0
	v_exp_f32_e32 v12, v72
	v_add_f32_e32 v5, v8, v5
	v_cndmask_b32_e32 v9, 0, v9, vcc
	v_cmp_le_u32_e32 vcc, v0, v2
	v_add_u32_e32 v0, s86, v0
	v_exp_f32_e32 v13, v73
	v_add_f32_e32 v5, v9, v5
	v_cndmask_b32_e32 v10, 0, v10, vcc
	v_cmp_le_u32_e32 vcc, v0, v2
	v_add_u32_e32 v0, s68, v0
	v_exp_f32_e32 v14, v74
	v_add_f32_e32 v5, v10, v5
	v_cndmask_b32_e32 v11, 0, v11, vcc
	v_cmp_le_u32_e32 vcc, v0, v2
	v_add_u32_e32 v0, s86, v0
	v_exp_f32_e32 v15, v75
	v_add_f32_e32 v5, v11, v5
	v_cndmask_b32_e32 v12, 0, v12, vcc
	v_cmp_le_u32_e32 vcc, v0, v2
	v_add_u32_e32 v0, s86, v0
	v_exp_f32_e32 v64, v76
	v_add_f32_e32 v5, v12, v5
	v_cndmask_b32_e32 v13, 0, v13, vcc
	v_cmp_le_u32_e32 vcc, v0, v2
	v_add_u32_e32 v0, s86, v0
	v_exp_f32_e32 v65, v77
	v_add_f32_e32 v5, v13, v5
	v_cndmask_b32_e32 v14, 0, v14, vcc
	v_cmp_le_u32_e32 vcc, v0, v2
	v_add_u32_e32 v0, s68, v0
	v_exp_f32_e32 v66, v78
	v_add_f32_e32 v5, v14, v5
	v_cndmask_b32_e32 v15, 0, v15, vcc
	v_cmp_le_u32_e32 vcc, v0, v2
	v_add_u32_e32 v0, s86, v0
	v_exp_f32_e32 v67, v79
	v_add_f32_e32 v5, v15, v5
	v_cndmask_b32_e32 v64, 0, v64, vcc
	v_cmp_le_u32_e32 vcc, v0, v2
	v_add_u32_e32 v0, s86, v0
	v_add_f32_e32 v5, v64, v5
	v_cndmask_b32_e32 v65, 0, v65, vcc
	v_cmp_le_u32_e32 vcc, v0, v2
	v_add_u32_e32 v0, s86, v0
	v_add_f32_e32 v5, v65, v5
	v_cndmask_b32_e32 v66, 0, v66, vcc
	v_cmp_le_u32_e32 vcc, v0, v2
	v_add_f32_e32 v5, v66, v5
	s_waitcnt lgkmcnt(0)
	s_add_i32 s86, s93, 1
	v_cndmask_b32_e32 v0, 0, v67, vcc
	v_add_f32_e32 v2, v0, v5
	v_add_f32_e32 v171, v171, v2
	v_cvt_pk_bf16_f32 v2, v4, v3
	v_cvt_pk_bf16_f32 v3, v6, v7
	v_cvt_pk_bf16_f32 v5, v10, v11
	v_cvt_pk_bf16_f32 v6, v12, v13
	v_cvt_pk_bf16_f32 v4, v8, v9
	v_cvt_pk_bf16_f32 v7, v14, v15
	v_cvt_pk_bf16_f32 v8, v64, v65
	v_cvt_pk_bf16_f32 v9, v66, v0
	s_cmp_gt_u32 s86, 32
	s_nop 0
	v_mfma_f32_32x32x16_bf16 v[32:47], v[180:183], v[2:5], v[32:47]
	v_mfma_f32_32x32x16_bf16 v[32:47], v[184:187], v[6:9], v[32:47]
	v_mfma_f32_32x32x16_bf16 v[16:31], v[188:191], v[2:5], v[16:31]
	v_mfma_f32_32x32x16_bf16 v[16:31], v[192:195], v[6:9], v[16:31]
	s_cbranch_scc1 .LBB0_139
	s_andn2_b64 vcc, exec, s[84:85]
	s_mov_b32 s84, 1
	s_cbranch_vccnz .LBB0_159
	s_cmp_gt_u32 s93, 27
	s_mov_b64 s[68:69], -1
	s_cbranch_scc0 .LBB0_157
	s_sub_i32 s85, s93, 27
	s_mov_b64 s[68:69], 0

.LBB0_160:
	s_waitcnt vmcnt(12)
	v_mfma_f32_32x32x16_bf16 v[64:79], v[120:123], v[80:83], v[48:63]
	s_cmp_gt_u32 s86, 30
	s_waitcnt vmcnt(11)
	ds_write_b128 v172, v[144:147] offset:4608
	s_waitcnt vmcnt(10)
	ds_write_b128 v173, v[148:151] offset:4608
	s_waitcnt vmcnt(9)
	ds_write_b128 v174, v[152:155] offset:4608
	s_waitcnt vmcnt(8)
	ds_write_b128 v175, v[156:159] offset:4608
	v_mfma_f32_32x32x16_bf16 v[64:79], v[124:127], v[84:87], v[64:79]
	ds_read_b64_tr_b16 v[180:181], v176 offset:4608
	ds_read_b64_tr_b16 v[182:183], v176 offset:5760
	v_mfma_f32_32x32x16_bf16 v[64:79], v[128:131], v[88:91], v[64:79]
	ds_read_b64_tr_b16 v[184:185], v176 offset:6912
	ds_read_b64_tr_b16 v[186:187], v176 offset:8064
	ds_read_b64_tr_b16 v[188:189], v176 offset:4672
	ds_read_b64_tr_b16 v[190:191], v176 offset:5824
	v_mfma_f32_32x32x16_bf16 v[64:79], v[132:135], v[92:95], v[64:79]
	ds_read_b64_tr_b16 v[192:193], v176 offset:6976
	ds_read_b64_tr_b16 v[194:195], v176 offset:8128
	s_cbranch_scc1 .LBB0_138
	s_cmp_lt_u32 s93, 18
	s_cbranch_scc1 .LBB0_136
	s_cmp_gt_u32 s93, 24
	s_mov_b64 s[68:69], -1
	s_cbranch_scc0 .LBB0_164
	s_sub_i32 s86, s93, 25
	s_mov_b64 s[68:69], 0
